# grid barrier acquire: wave 1 issues the agent-scope L1 invalidate at arrival and waits for it while wave 0 runs the counter protocol (every CU still acquires once per barrier; the invalidate latency o
# baseline (speedup 1.0000x reference)
.LBB0_1160:
	s_cmp_ge_i32 s66, s26
	s_cbranch_scc0 .LBB0_1216
	s_waitcnt vmcnt(0)
	v_readlane_b32 s0, v254, 0
	v_readlane_b32 s1, v254, 1
	s_andn2_b64 vcc, exec, s[0:1]
	s_waitcnt vmcnt(0)
	s_barrier
	s_cmp_eq_u32 s48, 64
	s_cbranch_scc0 .Lgb_noinv
	buffer_inv sc1
	s_waitcnt vmcnt(0)
.Lgb_noinv:
	s_cbranch_vccnz .LBB0_1215
	v_mbcnt_lo_u32_b32 v0, -1, 0
	v_mbcnt_hi_u32_b32 v0, -1, v0
	v_cmp_eq_u32_e32 vcc, 0, v0
	s_and_saveexec_b64 s[4:5], vcc
	s_cbranch_execz .LBB0_1214
	v_readlane_b32 s6, v254, 18
	v_readlane_b32 s7, v254, 19
	s_getreg_b32 s8, hwreg(HW_REG_XCC_ID, 0, 4)
	s_and_b32 s8, s8, 15
	v_readlane_b32 s9, v255, 21
	v_readlane_b32 s10, v255, 22
	v_readlane_b32 s11, v255, 23
	v_mov_b32_e32 v1, 0
	v_mov_b32_e32 v2, 1
	s_add_u32 s18, s6, 0x3400
	s_addc_u32 s19, s7, 0
	s_cmp_lg_u32 s9, 0
	s_cbranch_scc1 .Lgb_have_counts
	v_readlane_b32 s12, v255, 7
	s_add_u32 s16, s6, 0x400
	s_addc_u32 s17, s7, 0
	s_mov_b32 s13, 0

.Lgb_done:
	v_writelane_b32 v255, s12, 21
